# GEMM K-loop heads aligned to 64 bytes
# speedup vs baseline: 1.0123x; 1.0123x over previous
; template <class Epi, class Sched>
; __device__ __forceinline__ void gemm_phase(LAS unsigned char* lds, const Gemm g, const Sched& S, const Epi& E) {
;     ...
;         const bool has_next = S.next(ui + 1, nxt);
;         const size_t nko = (has_next && nxt.kc > 0) ? (size_t)nxt.kc * nts * kstep : 0;
;         const char* nA = has_next ? (const char*)g.A + (size_t)nxt.pm * tstep + nko : cA; const char* nB = has_next ? (const char*)g.Bt + (size_t)nxt.pn * tstep + nko : cB;
;         const int nt = cur.kc >= 0 ? nts : ntf;
;         for (int t = 0; t < nt; t += 2) {
;     ...
; #pragma unroll
;         for (int a = 0; a < 2; ++a)
; #pragma unroll
;             for (int b = 0; b < 2; ++b)
; #pragma unroll
;                 for (int m = 0; m < 4; ++m)
; #pragma unroll
;                     for (int n = 0; n < 2; ++n) acc[a][b][m][n] = (f32x4){0.f, 0.f, 0.f, 0.f};
.LBB0_502:
	s_ashr_i32 s51, s50, 31
	s_lshl_b64 s[12:13], s[50:51], 19
	s_add_u32 s54, s92, s12
	s_addc_u32 s55, s93, s13
	s_and_b64 s[12:13], s[38:39], exec
	s_cselect_b32 s7, s55, s15
	s_cselect_b32 s8, s54, s14
	s_ashr_i32 s53, s52, 31
	s_lshl_b64 s[12:13], s[52:53], 19
	s_add_u32 s56, s24, s12
	s_addc_u32 s57, s25, s13
	s_and_b64 s[12:13], s[38:39], exec
	s_cselect_b32 s12, s57, s17
	s_cselect_b32 s13, s56, s16
	s_add_u32 s14, s14, 0x40080
	s_addc_u32 s15, s15, 0
	s_add_u32 s21, s16, 0x100
	v_mov_b32_e32 v0, 0
	s_addc_u32 s33, s17, 0
	s_mov_b32 s40, -2
	v_mov_b32_e32 v1, v0
	s_waitcnt lgkmcnt(0)
	v_mov_b32_e32 v2, v0
	v_mov_b32_e32 v3, v0
	v_mov_b32_e32 v4, v0
	v_mov_b32_e32 v5, v0
	v_mov_b32_e32 v6, v0
	v_mov_b32_e32 v7, v0
	v_mov_b32_e32 v16, v0
	v_mov_b32_e32 v17, v0
	v_mov_b32_e32 v18, v0
	v_mov_b32_e32 v19, v0
	v_mov_b32_e32 v20, v0
	v_mov_b32_e32 v21, v0
	v_mov_b32_e32 v22, v0
	v_mov_b32_e32 v23, v0
	v_mov_b32_e32 v32, v0
	v_mov_b32_e32 v33, v0
	v_mov_b32_e32 v34, v0
	v_mov_b32_e32 v35, v0
	v_mov_b32_e32 v36, v0
	v_mov_b32_e32 v37, v0
	v_mov_b32_e32 v38, v0
	v_mov_b32_e32 v39, v0
	v_mov_b32_e32 v48, v0
	v_mov_b32_e32 v49, v0
	v_mov_b32_e32 v50, v0
	v_mov_b32_e32 v51, v0
	v_mov_b32_e32 v52, v0
	v_mov_b32_e32 v53, v0
	v_mov_b32_e32 v54, v0
	v_mov_b32_e32 v55, v0
	v_mov_b32_e32 v8, v0
	v_mov_b32_e32 v9, v0
	v_mov_b32_e32 v10, v0
	v_mov_b32_e32 v11, v0
	v_mov_b32_e32 v12, v0
	v_mov_b32_e32 v13, v0
	v_mov_b32_e32 v14, v0
	v_mov_b32_e32 v15, v0
	v_mov_b32_e32 v24, v0
	v_mov_b32_e32 v25, v0
	v_mov_b32_e32 v26, v0
	v_mov_b32_e32 v27, v0
	v_mov_b32_e32 v28, v0
	v_mov_b32_e32 v29, v0
	v_mov_b32_e32 v30, v0
	v_mov_b32_e32 v31, v0
	v_mov_b32_e32 v40, v0
	v_mov_b32_e32 v41, v0
	v_mov_b32_e32 v42, v0
	v_mov_b32_e32 v43, v0
	v_mov_b32_e32 v44, v0
	v_mov_b32_e32 v45, v0
	v_mov_b32_e32 v46, v0
	v_mov_b32_e32 v47, v0
	v_mov_b32_e32 v56, v0
	v_mov_b32_e32 v57, v0
	v_mov_b32_e32 v58, v0
	v_mov_b32_e32 v59, v0
	v_mov_b32_e32 v60, v0
	v_mov_b32_e32 v61, v0
	v_mov_b32_e32 v62, v0
	v_mov_b32_e32 v63, v0
	v_mov_b32_e32 v64, v0
	v_mov_b32_e32 v65, v0
	v_mov_b32_e32 v66, v0
	v_mov_b32_e32 v67, v0
	v_mov_b32_e32 v68, v0
	v_mov_b32_e32 v69, v0
	v_mov_b32_e32 v70, v0
	v_mov_b32_e32 v71, v0
	v_mov_b32_e32 v96, v0
	v_mov_b32_e32 v97, v0
	v_mov_b32_e32 v98, v0
	v_mov_b32_e32 v99, v0
	v_mov_b32_e32 v100, v0
	v_mov_b32_e32 v101, v0
	v_mov_b32_e32 v102, v0
	v_mov_b32_e32 v103, v0
	v_mov_b32_e32 v112, v0
	v_mov_b32_e32 v113, v0
	v_mov_b32_e32 v114, v0
	v_mov_b32_e32 v115, v0
	v_mov_b32_e32 v116, v0
	v_mov_b32_e32 v117, v0
	v_mov_b32_e32 v118, v0
	v_mov_b32_e32 v119, v0
	v_mov_b32_e32 v128, v0
	v_mov_b32_e32 v129, v0
	v_mov_b32_e32 v130, v0
	v_mov_b32_e32 v131, v0
	v_mov_b32_e32 v132, v0
	v_mov_b32_e32 v133, v0
	v_mov_b32_e32 v134, v0
	v_mov_b32_e32 v135, v0
	v_mov_b32_e32 v88, v0
	v_mov_b32_e32 v89, v0
	v_mov_b32_e32 v90, v0
	v_mov_b32_e32 v91, v0
	v_mov_b32_e32 v92, v0
	v_mov_b32_e32 v93, v0
	v_mov_b32_e32 v94, v0
	v_mov_b32_e32 v95, v0
	v_mov_b32_e32 v104, v0
	v_mov_b32_e32 v105, v0
	v_mov_b32_e32 v106, v0
	v_mov_b32_e32 v107, v0
	v_mov_b32_e32 v108, v0
	v_mov_b32_e32 v109, v0
	v_mov_b32_e32 v110, v0
	v_mov_b32_e32 v111, v0
	v_mov_b32_e32 v120, v0
	v_mov_b32_e32 v121, v0
	v_mov_b32_e32 v122, v0
	v_mov_b32_e32 v123, v0
	v_mov_b32_e32 v124, v0
	v_mov_b32_e32 v125, v0
	v_mov_b32_e32 v126, v0
	v_mov_b32_e32 v127, v0
	v_mov_b32_e32 v136, v0
	v_mov_b32_e32 v137, v0
	v_mov_b32_e32 v138, v0
	v_mov_b32_e32 v139, v0
	v_mov_b32_e32 v140, v0
	v_mov_b32_e32 v141, v0
	v_mov_b32_e32 v142, v0
	v_mov_b32_e32 v143, v0
	.p2align	6

; template <class Epi, class Sched>
; __device__ __forceinline__ void gemm_phase(LAS unsigned char* lds, const Gemm g, const Sched& S, const Epi& E) {
;     ...
;         const int nt = cur.kc >= 0 ? nts : ntf;
;         for (int t = 0; t < nt; t += 2) {
;     ...
; #pragma unroll
;         for (int a = 0; a < 2; ++a)
; #pragma unroll
;             for (int b = 0; b < 2; ++b)
; #pragma unroll
;                 for (int m = 0; m < 4; ++m)
; #pragma unroll
;                     for (int n = 0; n < 2; ++n) acc[a][b][m][n] = (f32x4){0.f, 0.f, 0.f, 0.f};
.LBB0_598:
	s_cmp_lt_i32 s78, 0
	s_cselect_b32 s8, s22, s23
	s_add_i32 s12, s8, -2
	s_add_u32 s6, s6, 0x80
	s_addc_u32 s7, s7, 0
	s_add_u32 s13, s14, 0x100
	v_mov_b32_e32 v0, 0
	s_mov_b32 s17, 0
	s_addc_u32 s16, s15, 0
	v_mov_b32_e32 v1, v0
	v_mov_b32_e32 v2, v0
	v_mov_b32_e32 v3, v0
	v_mov_b32_e32 v4, v0
	v_mov_b32_e32 v5, v0
	v_mov_b32_e32 v6, v0
	v_mov_b32_e32 v7, v0
	v_mov_b32_e32 v8, v0
	v_mov_b32_e32 v9, v0
	v_mov_b32_e32 v10, v0
	v_mov_b32_e32 v11, v0
	v_mov_b32_e32 v12, v0
	v_mov_b32_e32 v13, v0
	v_mov_b32_e32 v14, v0
	v_mov_b32_e32 v15, v0
	v_mov_b32_e32 v24, v0
	v_mov_b32_e32 v25, v0
	v_mov_b32_e32 v26, v0
	v_mov_b32_e32 v27, v0
	v_mov_b32_e32 v28, v0
	v_mov_b32_e32 v29, v0
	v_mov_b32_e32 v30, v0
	v_mov_b32_e32 v31, v0
	v_mov_b32_e32 v40, v0
	v_mov_b32_e32 v41, v0
	v_mov_b32_e32 v42, v0
	v_mov_b32_e32 v43, v0
	v_mov_b32_e32 v44, v0
	v_mov_b32_e32 v45, v0
	v_mov_b32_e32 v46, v0
	v_mov_b32_e32 v47, v0
	v_mov_b32_e32 v16, v0
	v_mov_b32_e32 v17, v0
	v_mov_b32_e32 v18, v0
	v_mov_b32_e32 v19, v0
	v_mov_b32_e32 v20, v0
	v_mov_b32_e32 v21, v0
	v_mov_b32_e32 v22, v0
	v_mov_b32_e32 v23, v0
	v_mov_b32_e32 v32, v0
	v_mov_b32_e32 v33, v0
	v_mov_b32_e32 v34, v0
	v_mov_b32_e32 v35, v0
	v_mov_b32_e32 v36, v0
	v_mov_b32_e32 v37, v0
	v_mov_b32_e32 v38, v0
	v_mov_b32_e32 v39, v0
	v_mov_b32_e32 v48, v0
	v_mov_b32_e32 v49, v0
	v_mov_b32_e32 v50, v0
	v_mov_b32_e32 v51, v0
	v_mov_b32_e32 v52, v0
	v_mov_b32_e32 v53, v0
	v_mov_b32_e32 v54, v0
	v_mov_b32_e32 v55, v0
	v_mov_b32_e32 v56, v0
	v_mov_b32_e32 v57, v0
	v_mov_b32_e32 v58, v0
	v_mov_b32_e32 v59, v0
	v_mov_b32_e32 v60, v0
	v_mov_b32_e32 v61, v0
	v_mov_b32_e32 v62, v0
	v_mov_b32_e32 v63, v0
	v_mov_b32_e32 v64, v0
	v_mov_b32_e32 v65, v0
	v_mov_b32_e32 v66, v0
	v_mov_b32_e32 v67, v0
	v_mov_b32_e32 v68, v0
	v_mov_b32_e32 v69, v0
	v_mov_b32_e32 v70, v0
	v_mov_b32_e32 v71, v0
	v_mov_b32_e32 v72, v0
	v_mov_b32_e32 v73, v0
	v_mov_b32_e32 v74, v0
	v_mov_b32_e32 v75, v0
	v_mov_b32_e32 v76, v0
	v_mov_b32_e32 v77, v0
	v_mov_b32_e32 v78, v0
	v_mov_b32_e32 v79, v0
	v_mov_b32_e32 v84, v0
	v_mov_b32_e32 v85, v0
	v_mov_b32_e32 v86, v0
	v_mov_b32_e32 v87, v0
	v_mov_b32_e32 v92, v0
	v_mov_b32_e32 v93, v0
	v_mov_b32_e32 v94, v0
	v_mov_b32_e32 v95, v0
	v_mov_b32_e32 v100, v0
	v_mov_b32_e32 v101, v0
	v_mov_b32_e32 v102, v0
	v_mov_b32_e32 v103, v0
	v_mov_b32_e32 v108, v0
	v_mov_b32_e32 v109, v0
	v_mov_b32_e32 v110, v0
	v_mov_b32_e32 v111, v0
	v_mov_b32_e32 v80, v0
	v_mov_b32_e32 v81, v0
	v_mov_b32_e32 v82, v0
	v_mov_b32_e32 v83, v0
	v_mov_b32_e32 v88, v0
	v_mov_b32_e32 v89, v0
	v_mov_b32_e32 v90, v0
	v_mov_b32_e32 v91, v0
	v_mov_b32_e32 v96, v0
	v_mov_b32_e32 v97, v0
	v_mov_b32_e32 v98, v0
	v_mov_b32_e32 v99, v0
	v_mov_b32_e32 v104, v0
	v_mov_b32_e32 v105, v0
	v_mov_b32_e32 v106, v0
	v_mov_b32_e32 v107, v0
	v_mov_b32_e32 v112, v0
	v_mov_b32_e32 v113, v0
	v_mov_b32_e32 v114, v0
	v_mov_b32_e32 v115, v0
	v_mov_b32_e32 v116, v0
	v_mov_b32_e32 v117, v0
	v_mov_b32_e32 v118, v0
	v_mov_b32_e32 v119, v0
	v_mov_b32_e32 v120, v0
	v_mov_b32_e32 v121, v0
	v_mov_b32_e32 v122, v0
	v_mov_b32_e32 v123, v0
	v_mov_b32_e32 v124, v0
	v_mov_b32_e32 v125, v0
	v_mov_b32_e32 v126, v0
	v_mov_b32_e32 v127, v0
	.p2align	6

; template <class Epi, class Sched>
; __device__ __forceinline__ void gemm_phase(LAS unsigned char* lds, const Gemm g, const Sched& S, const Epi& E) {
;     ...
;         const bool has_next = S.next(ui + 1, nxt);
;         const size_t nko = (has_next && nxt.kc > 0) ? (size_t)nxt.kc * nts * kstep : 0;
;         const char* nA = has_next ? (const char*)g.A + (size_t)nxt.pm * tstep + nko : cA; const char* nB = has_next ? (const char*)g.Bt + (size_t)nxt.pn * tstep + nko : cB;
;         const int nt = cur.kc >= 0 ? nts : ntf;
;         for (int t = 0; t < nt; t += 2) {
;     ...
; #pragma unroll
;         for (int a = 0; a < 2; ++a)
; #pragma unroll
;             for (int b = 0; b < 2; ++b)
; #pragma unroll
;                 for (int m = 0; m < 4; ++m)
; #pragma unroll
;                     for (int n = 0; n < 2; ++n) acc[a][b][m][n] = (f32x4){0.f, 0.f, 0.f, 0.f};
.LBB0_743:
	s_ashr_i32 s15, s14, 31
	s_lshl_b64 s[18:19], s[14:15], 19
	s_add_u32 s18, s92, s18
	s_addc_u32 s19, s93, s19
	s_and_b64 s[20:21], s[38:39], exec
	s_cselect_b32 s15, s19, s23
	s_cselect_b32 s44, s18, s22
	s_ashr_i32 s17, s16, 31
	s_lshl_b64 s[20:21], s[16:17], 19
	s_add_u32 s20, s9, s20
	s_addc_u32 s21, s12, s21
	s_and_b64 s[26:27], s[38:39], exec
	s_cselect_b32 s17, s21, s25
	s_cselect_b32 s45, s20, s24
	s_add_u32 s22, s22, 0x40080
	s_addc_u32 s23, s23, 0
	s_add_u32 s46, s24, 0x100
	v_mov_b32_e32 v4, 0
	s_addc_u32 s47, s25, 0
	s_mov_b32 s48, -2
	v_mov_b32_e32 v5, v4
	v_mov_b32_e32 v6, v4
	v_mov_b32_e32 v7, v4
	v_mov_b32_e32 v0, v4
	v_mov_b32_e32 v1, v4
	v_mov_b32_e32 v2, v4
	v_mov_b32_e32 v3, v4
	v_mov_b32_e32 v20, v4
	v_mov_b32_e32 v21, v4
	v_mov_b32_e32 v22, v4
	v_mov_b32_e32 v23, v4
	v_mov_b32_e32 v16, v4
	v_mov_b32_e32 v17, v4
	v_mov_b32_e32 v18, v4
	v_mov_b32_e32 v19, v4
	v_mov_b32_e32 v36, v4
	v_mov_b32_e32 v37, v4
	v_mov_b32_e32 v38, v4
	v_mov_b32_e32 v39, v4
	v_mov_b32_e32 v32, v4
	v_mov_b32_e32 v33, v4
	v_mov_b32_e32 v34, v4
	v_mov_b32_e32 v35, v4
	v_mov_b32_e32 v52, v4
	v_mov_b32_e32 v53, v4
	v_mov_b32_e32 v54, v4
	v_mov_b32_e32 v55, v4
	v_mov_b32_e32 v48, v4
	v_mov_b32_e32 v49, v4
	v_mov_b32_e32 v50, v4
	v_mov_b32_e32 v51, v4
	v_mov_b32_e32 v8, v4
	v_mov_b32_e32 v9, v4
	v_mov_b32_e32 v10, v4
	v_mov_b32_e32 v11, v4
	v_mov_b32_e32 v12, v4
	v_mov_b32_e32 v13, v4
	v_mov_b32_e32 v14, v4
	v_mov_b32_e32 v15, v4
	v_mov_b32_e32 v24, v4
	v_mov_b32_e32 v25, v4
	v_mov_b32_e32 v26, v4
	v_mov_b32_e32 v27, v4
	v_mov_b32_e32 v28, v4
	v_mov_b32_e32 v29, v4
	v_mov_b32_e32 v30, v4
	v_mov_b32_e32 v31, v4
	v_mov_b32_e32 v40, v4
	v_mov_b32_e32 v41, v4
	v_mov_b32_e32 v42, v4
	v_mov_b32_e32 v43, v4
	v_mov_b32_e32 v44, v4
	v_mov_b32_e32 v45, v4
	v_mov_b32_e32 v46, v4
	v_mov_b32_e32 v47, v4
	v_mov_b32_e32 v56, v4
	v_mov_b32_e32 v57, v4
	v_mov_b32_e32 v58, v4
	v_mov_b32_e32 v59, v4
	v_mov_b32_e32 v60, v4
	v_mov_b32_e32 v61, v4
	v_mov_b32_e32 v62, v4
	v_mov_b32_e32 v63, v4
	v_mov_b32_e32 v68, v4
	v_mov_b32_e32 v69, v4
	v_mov_b32_e32 v70, v4
	v_mov_b32_e32 v71, v4
	v_mov_b32_e32 v64, v4
	v_mov_b32_e32 v65, v4
	v_mov_b32_e32 v66, v4
	v_mov_b32_e32 v67, v4
	v_mov_b32_e32 v84, v4
	v_mov_b32_e32 v85, v4
	v_mov_b32_e32 v86, v4
	v_mov_b32_e32 v87, v4
	v_mov_b32_e32 v80, v4
	v_mov_b32_e32 v81, v4
	v_mov_b32_e32 v82, v4
	v_mov_b32_e32 v83, v4
	v_mov_b32_e32 v100, v4
	v_mov_b32_e32 v101, v4
	v_mov_b32_e32 v102, v4
	v_mov_b32_e32 v103, v4
	v_mov_b32_e32 v96, v4
	v_mov_b32_e32 v97, v4
	v_mov_b32_e32 v98, v4
	v_mov_b32_e32 v99, v4
	v_mov_b32_e32 v116, v4
	v_mov_b32_e32 v117, v4
	v_mov_b32_e32 v118, v4
	v_mov_b32_e32 v119, v4
	v_mov_b32_e32 v112, v4
	v_mov_b32_e32 v113, v4
	v_mov_b32_e32 v114, v4
	v_mov_b32_e32 v115, v4
	v_mov_b32_e32 v72, v4
	v_mov_b32_e32 v73, v4
	v_mov_b32_e32 v74, v4
	v_mov_b32_e32 v75, v4
	v_mov_b32_e32 v76, v4
	v_mov_b32_e32 v77, v4
	v_mov_b32_e32 v78, v4
	v_mov_b32_e32 v79, v4
	v_mov_b32_e32 v88, v4
	v_mov_b32_e32 v89, v4
	v_mov_b32_e32 v90, v4
	v_mov_b32_e32 v91, v4
	v_mov_b32_e32 v92, v4
	v_mov_b32_e32 v93, v4
	v_mov_b32_e32 v94, v4
	v_mov_b32_e32 v95, v4
	v_mov_b32_e32 v104, v4
	v_mov_b32_e32 v105, v4
	v_mov_b32_e32 v106, v4
	v_mov_b32_e32 v107, v4
	v_mov_b32_e32 v108, v4
	v_mov_b32_e32 v109, v4
	v_mov_b32_e32 v110, v4
	v_mov_b32_e32 v111, v4
	v_mov_b32_e32 v120, v4
	v_mov_b32_e32 v121, v4
	v_mov_b32_e32 v122, v4
	v_mov_b32_e32 v123, v4
	v_mov_b32_e32 v124, v4
	v_mov_b32_e32 v125, v4
	v_mov_b32_e32 v126, v4
	v_mov_b32_e32 v127, v4
	.p2align	6
